# phase 3 tail: 16 scalar row-sum v_add_f32 become 8 v_pk_add_f32 (same operands and order)
# speedup vs baseline: 1.0039x; 1.0006x over previous
; __device__ __forceinline__ void attn_tile(const bool BAND, AttnSmem& sm, u16* Qg, int qtok0, int hd, int nw, const u16* __restrict__ Kg, ...
;     ...
; #pragma unroll
;         for (int i = 0; i < 8; i++) { const f32v2 t2 = {pv[2 * i], pv[2 * i + 1]}; ls2 += t2; }
; #pragma unroll
;         for (int st = 0; st < 2; st++) {
;           union { uint32_t u[4]; bf16x8 b; } pf;
; #pragma unroll
;           for (int j = 0; j < 4; j++) pf.u[j] = pack2(pv[8 * st + 2 * j], pv[8 * st + 2 * j + 1]);
;           union { uint2 u[2]; bf16x8 b; } v0, v1;
;           const int kc = sb * 32 + 16 * st + 4 * h;
;           v0.u[0] = *(const uint2*)&sm.VT[cur][r][kc];
;           v0.u[1] = *(const uint2*)&sm.VT[cur][r][kc + 8];
;           v1.u[0] = *(const uint2*)&sm.VT[cur][32 + r][kc];
;           v1.u[1] = *(const uint2*)&sm.VT[cur][32 + r][kc + 8];
;           o0 = mfma32(v0.b, pf.b, o0);
;           o1 = mfma32(v1.b, pf.b, o1);
;         }
.Lp3_tail:
	v_pk_add_f32 v[34:35], v[134:135], v[34:35]
	v_cvt_pk_bf16_f32 v70, v50, v51
	v_pk_add_f32 v[34:35], v[36:37], v[34:35]
	v_cvt_pk_bf16_f32 v71, v52, v53
	v_pk_add_f32 v[34:35], v[38:39], v[34:35]
	v_cvt_pk_bf16_f32 v72, v54, v55
	v_pk_add_f32 v[34:35], v[40:41], v[34:35]
	v_cvt_pk_bf16_f32 v73, v56, v57
	v_pk_add_f32 v[34:35], v[42:43], v[34:35]
	v_cvt_pk_bf16_f32 v40, v62, v63
	v_pk_add_f32 v[38:39], v[44:45], v[34:35]
	s_waitcnt lgkmcnt(3)
	v_mfma_f32_32x32x16_bf16 v[2:17], v[212:215], v[70:73], v[2:17]
	v_pk_add_f32 v[38:39], v[46:47], v[38:39]
	v_cvt_pk_bf16_f32 v41, v64, v65
	v_pk_add_f32 v[46:47], v[48:49], v[38:39]
	v_cvt_pk_bf16_f32 v38, v58, v59
	v_cvt_pk_bf16_f32 v39, v60, v61
	s_waitcnt lgkmcnt(2)
	v_mfma_f32_32x32x16_bf16 v[18:33], v[216:219], v[70:73], v[18:33]
	s_waitcnt lgkmcnt(1)
	v_mfma_f32_32x32x16_bf16 v[2:17], v[220:223], v[38:41], v[2:17]
	v_pk_add_f32 v[34:35], v[46:47], v[50:51]
	v_pk_add_f32 v[34:35], v[52:53], v[34:35]
	v_pk_add_f32 v[34:35], v[54:55], v[34:35]
	v_pk_add_f32 v[34:35], v[56:57], v[34:35]
	s_waitcnt lgkmcnt(0)
	v_mfma_f32_32x32x16_bf16 v[18:33], v[224:227], v[38:41], v[18:33]
	v_pk_add_f32 v[34:35], v[58:59], v[34:35]
	v_pk_add_f32 v[34:35], v[60:61], v[34:35]
	v_pk_add_f32 v[34:35], v[62:63], v[34:35]
	v_pk_add_f32 v[134:135], v[64:65], v[34:35]
